# late pass: W2[0] also converted by a 2-deep pipelined routine (4 tiles per wave)
# baseline (speedup 1.0000x reference)
.Lgv_end:
.Lw2l_begin:
	s_cmp_eq_u32 s99, 1
	s_cbranch_scc1 .Lw2l_end
	v_readlane_b32 s43, v255, 8
	v_lshrrev_b32_e32 v2, 3, v244
	v_and_b32_e32 v3, 7, v244
	v_lshlrev_b32_e32 v4, 13, v2
	v_lshl_add_u32 v4, v3, 4, v4
	s_lshl_b32 s31, s85, 14
	v_lshlrev_b32_e32 v5, 7, v2
	v_add_u32_e32 v5, s31, v5
	v_xor_b32_e32 v6, 0, v3
	v_lshl_add_u32 v110, v6, 4, v5
	v_xor_b32_e32 v6, 1, v3
	v_lshl_add_u32 v111, v6, 4, v5
	v_xor_b32_e32 v6, 2, v3
	v_lshl_add_u32 v112, v6, 4, v5
	v_xor_b32_e32 v6, 3, v3
	v_lshl_add_u32 v113, v6, 4, v5
	v_xor_b32_e32 v6, 4, v3
	v_lshl_add_u32 v114, v6, 4, v5
	v_xor_b32_e32 v6, 5, v3
	v_lshl_add_u32 v115, v6, 4, v5
	v_xor_b32_e32 v6, 6, v3
	v_lshl_add_u32 v116, v6, 4, v5
	v_xor_b32_e32 v6, 7, v3
	v_lshl_add_u32 v117, v6, 4, v5
	v_lshlrev_b32_e32 v7, 10, v3
	v_add_u32_e32 v7, s31, v7
	v_add_u32_e32 v8, 0, v2
	v_lshrrev_b32_e32 v9, 2, v8
	v_xor_b32_e32 v9, v9, v3
	v_and_b32_e32 v8, 3, v8
	v_lshl_add_u32 v8, v9, 2, v8
	v_lshl_add_u32 v118, v8, 2, v7
	v_add_u32_e32 v8, 8, v2
	v_lshrrev_b32_e32 v9, 2, v8
	v_xor_b32_e32 v9, v9, v3
	v_and_b32_e32 v8, 3, v8
	v_lshl_add_u32 v8, v9, 2, v8
	v_lshl_add_u32 v119, v8, 2, v7
	v_add_u32_e32 v8, 16, v2
	v_lshrrev_b32_e32 v9, 2, v8
	v_xor_b32_e32 v9, v9, v3
	v_and_b32_e32 v8, 3, v8
	v_lshl_add_u32 v8, v9, 2, v8
	v_lshl_add_u32 v120, v8, 2, v7
	v_add_u32_e32 v8, 24, v2
	v_lshrrev_b32_e32 v9, 2, v8
	v_xor_b32_e32 v9, v9, v3
	v_and_b32_e32 v8, 3, v8
	v_lshl_add_u32 v8, v9, 2, v8
	v_lshl_add_u32 v121, v8, 2, v7
	s_load_dwordx2 s[26:27], s[86:87], 0xd8
	s_load_dwordx2 s[28:29], s[86:87], 0x118
	s_mov_b32 s30, s43
	v_lshlrev_b32_e32 v74, 14, v2
	v_lshl_add_u32 v74, v3, 4, v74
	v_add_u32_e32 v75, 0x20000, v74
	v_add_u32_e32 v76, 0x40000, v74
	v_add_u32_e32 v77, 0x60000, v74
	s_waitcnt lgkmcnt(0)
	s_add_u32 s28, s28, 0x3200000
	s_addc_u32 s29, s29, 0
	s_lshr_b32 s46, s30, 6
	s_and_b32 s47, s30, 63
	s_mov_b32 s40, s30
	s_lshl_b32 s36, s46, 19
	s_lshl_b32 s37, s47, 7
	s_add_i32 s36, s36, s37
	s_add_u32 s38, s26, s36
	s_addc_u32 s39, s27, 0
	global_load_dwordx4 v[10:13], v4, s[38:39] nt
	s_add_u32 s38, s38, 0x10000
	s_addc_u32 s39, s39, 0
	global_load_dwordx4 v[14:17], v4, s[38:39] nt
	s_add_u32 s38, s38, 0x10000
	s_addc_u32 s39, s39, 0
	global_load_dwordx4 v[18:21], v4, s[38:39] nt
	s_add_u32 s38, s38, 0x10000
	s_addc_u32 s39, s39, 0
	global_load_dwordx4 v[22:25], v4, s[38:39] nt
	s_add_u32 s38, s38, 0x10000
	s_addc_u32 s39, s39, 0
	global_load_dwordx4 v[26:29], v4, s[38:39] nt
	s_add_u32 s38, s38, 0x10000
	s_addc_u32 s39, s39, 0
	global_load_dwordx4 v[30:33], v4, s[38:39] nt
	s_add_u32 s38, s38, 0x10000
	s_addc_u32 s39, s39, 0
	global_load_dwordx4 v[34:37], v4, s[38:39] nt
	s_add_u32 s38, s38, 0x10000
	s_addc_u32 s39, s39, 0
	global_load_dwordx4 v[38:41], v4, s[38:39] nt
	s_addk_i32 s30, 0x800
	s_and_b32 s30, s30, 0x1fff
	s_lshr_b32 s46, s30, 6
	s_and_b32 s47, s30, 63
	s_mov_b32 s41, s30
	s_lshl_b32 s36, s46, 19
	s_lshl_b32 s37, s47, 7
	s_add_i32 s36, s36, s37
	s_add_u32 s38, s26, s36
	s_addc_u32 s39, s27, 0
	global_load_dwordx4 v[42:45], v4, s[38:39] nt
	s_add_u32 s38, s38, 0x10000
	s_addc_u32 s39, s39, 0
	global_load_dwordx4 v[46:49], v4, s[38:39] nt
	s_add_u32 s38, s38, 0x10000
	s_addc_u32 s39, s39, 0
	global_load_dwordx4 v[50:53], v4, s[38:39] nt
	s_add_u32 s38, s38, 0x10000
	s_addc_u32 s39, s39, 0
	global_load_dwordx4 v[54:57], v4, s[38:39] nt
	s_add_u32 s38, s38, 0x10000
	s_addc_u32 s39, s39, 0
	global_load_dwordx4 v[58:61], v4, s[38:39] nt
	s_add_u32 s38, s38, 0x10000
	s_addc_u32 s39, s39, 0
	global_load_dwordx4 v[62:65], v4, s[38:39] nt
	s_add_u32 s38, s38, 0x10000
	s_addc_u32 s39, s39, 0
	global_load_dwordx4 v[66:69], v4, s[38:39] nt
	s_add_u32 s38, s38, 0x10000
	s_addc_u32 s39, s39, 0
	global_load_dwordx4 v[70:73], v4, s[38:39] nt
	s_addk_i32 s30, 0x800
	s_and_b32 s30, s30, 0x1fff
	s_waitcnt vmcnt(8)
	ds_write_b128 v110, v[10:13]
	ds_write_b128 v111, v[14:17] offset:1024
	ds_write_b128 v112, v[18:21] offset:2048
	ds_write_b128 v113, v[22:25] offset:3072
	ds_write_b128 v114, v[26:29] offset:4096
	ds_write_b128 v115, v[30:33] offset:5120
	ds_write_b128 v116, v[34:37] offset:6144
	ds_write_b128 v117, v[38:41] offset:7168
	ds_read2_b32 v[10:11], v118 offset1:32
	ds_read2_b32 v[12:13], v118 offset0:64 offset1:96
	ds_read2_b32 v[14:15], v118 offset0:128 offset1:160
	ds_read2_b32 v[16:17], v118 offset0:192 offset1:224
	ds_read2_b32 v[18:19], v119 offset1:32
	ds_read2_b32 v[20:21], v119 offset0:64 offset1:96
	ds_read2_b32 v[22:23], v119 offset0:128 offset1:160
	ds_read2_b32 v[24:25], v119 offset0:192 offset1:224
	ds_read2_b32 v[26:27], v120 offset1:32
	ds_read2_b32 v[28:29], v120 offset0:64 offset1:96
	ds_read2_b32 v[30:31], v120 offset0:128 offset1:160
	ds_read2_b32 v[32:33], v120 offset0:192 offset1:224
	ds_read2_b32 v[34:35], v121 offset1:32
	ds_read2_b32 v[36:37], v121 offset0:64 offset1:96
	ds_read2_b32 v[38:39], v121 offset0:128 offset1:160
	ds_read2_b32 v[40:41], v121 offset0:192 offset1:224
	s_lshr_b32 s46, s40, 6
	s_and_b32 s47, s40, 63
	s_lshl_b32 s36, s47, 19
	s_lshl_b32 s37, s46, 7
	s_add_i32 s36, s36, s37
	s_add_u32 s38, s28, s36
	s_addc_u32 s39, s29, 0
	s_waitcnt lgkmcnt(12)
	v_cvt_pk_bf16_f32 v78, v10, v11
	v_cvt_pk_bf16_f32 v79, v12, v13
	v_cvt_pk_bf16_f32 v80, v14, v15
	v_cvt_pk_bf16_f32 v81, v16, v17
	s_waitcnt lgkmcnt(8)
	v_cvt_pk_bf16_f32 v82, v18, v19
	v_cvt_pk_bf16_f32 v83, v20, v21
	v_cvt_pk_bf16_f32 v84, v22, v23
	v_cvt_pk_bf16_f32 v85, v24, v25
	s_waitcnt lgkmcnt(4)
	v_cvt_pk_bf16_f32 v86, v26, v27
	v_cvt_pk_bf16_f32 v87, v28, v29
	v_cvt_pk_bf16_f32 v88, v30, v31
	v_cvt_pk_bf16_f32 v89, v32, v33
	s_waitcnt lgkmcnt(0)
	v_cvt_pk_bf16_f32 v90, v34, v35
	v_cvt_pk_bf16_f32 v91, v36, v37
	v_cvt_pk_bf16_f32 v92, v38, v39
	v_cvt_pk_bf16_f32 v93, v40, v41
	global_store_dwordx4 v74, v[78:81], s[38:39]
	global_store_dwordx4 v75, v[82:85], s[38:39]
	global_store_dwordx4 v76, v[86:89], s[38:39]
	global_store_dwordx4 v77, v[90:93], s[38:39]
	s_lshr_b32 s46, s30, 6
	s_and_b32 s47, s30, 63
	s_mov_b32 s40, s30
	s_lshl_b32 s36, s46, 19
	s_lshl_b32 s37, s47, 7
	s_add_i32 s36, s36, s37
	s_add_u32 s38, s26, s36
	s_addc_u32 s39, s27, 0
	global_load_dwordx4 v[10:13], v4, s[38:39] nt
	s_add_u32 s38, s38, 0x10000
	s_addc_u32 s39, s39, 0
	global_load_dwordx4 v[14:17], v4, s[38:39] nt
	s_add_u32 s38, s38, 0x10000
	s_addc_u32 s39, s39, 0
	global_load_dwordx4 v[18:21], v4, s[38:39] nt
	s_add_u32 s38, s38, 0x10000
	s_addc_u32 s39, s39, 0
	global_load_dwordx4 v[22:25], v4, s[38:39] nt
	s_add_u32 s38, s38, 0x10000
	s_addc_u32 s39, s39, 0
	global_load_dwordx4 v[26:29], v4, s[38:39] nt
	s_add_u32 s38, s38, 0x10000
	s_addc_u32 s39, s39, 0
	global_load_dwordx4 v[30:33], v4, s[38:39] nt
	s_add_u32 s38, s38, 0x10000
	s_addc_u32 s39, s39, 0
	global_load_dwordx4 v[34:37], v4, s[38:39] nt
	s_add_u32 s38, s38, 0x10000
	s_addc_u32 s39, s39, 0
	global_load_dwordx4 v[38:41], v4, s[38:39] nt
	s_addk_i32 s30, 0x800
	s_and_b32 s30, s30, 0x1fff
	s_waitcnt vmcnt(12)
	ds_write_b128 v110, v[42:45]
	ds_write_b128 v111, v[46:49] offset:1024
	ds_write_b128 v112, v[50:53] offset:2048
	ds_write_b128 v113, v[54:57] offset:3072
	ds_write_b128 v114, v[58:61] offset:4096
	ds_write_b128 v115, v[62:65] offset:5120
	ds_write_b128 v116, v[66:69] offset:6144
	ds_write_b128 v117, v[70:73] offset:7168
	ds_read2_b32 v[42:43], v118 offset1:32
	ds_read2_b32 v[44:45], v118 offset0:64 offset1:96
	ds_read2_b32 v[46:47], v118 offset0:128 offset1:160
	ds_read2_b32 v[48:49], v118 offset0:192 offset1:224
	ds_read2_b32 v[50:51], v119 offset1:32
	ds_read2_b32 v[52:53], v119 offset0:64 offset1:96
	ds_read2_b32 v[54:55], v119 offset0:128 offset1:160
	ds_read2_b32 v[56:57], v119 offset0:192 offset1:224
	ds_read2_b32 v[58:59], v120 offset1:32
	ds_read2_b32 v[60:61], v120 offset0:64 offset1:96
	ds_read2_b32 v[62:63], v120 offset0:128 offset1:160
	ds_read2_b32 v[64:65], v120 offset0:192 offset1:224
	ds_read2_b32 v[66:67], v121 offset1:32
	ds_read2_b32 v[68:69], v121 offset0:64 offset1:96
	ds_read2_b32 v[70:71], v121 offset0:128 offset1:160
	ds_read2_b32 v[72:73], v121 offset0:192 offset1:224
	s_lshr_b32 s46, s41, 6
	s_and_b32 s47, s41, 63
	s_lshl_b32 s36, s47, 19
	s_lshl_b32 s37, s46, 7
	s_add_i32 s36, s36, s37
	s_add_u32 s38, s28, s36
	s_addc_u32 s39, s29, 0
	s_waitcnt lgkmcnt(12)
	v_cvt_pk_bf16_f32 v94, v42, v43
	v_cvt_pk_bf16_f32 v95, v44, v45
	v_cvt_pk_bf16_f32 v96, v46, v47
	v_cvt_pk_bf16_f32 v97, v48, v49
	s_waitcnt lgkmcnt(8)
	v_cvt_pk_bf16_f32 v98, v50, v51
	v_cvt_pk_bf16_f32 v99, v52, v53
	v_cvt_pk_bf16_f32 v100, v54, v55
	v_cvt_pk_bf16_f32 v101, v56, v57
	s_waitcnt lgkmcnt(4)
	v_cvt_pk_bf16_f32 v102, v58, v59
	v_cvt_pk_bf16_f32 v103, v60, v61
	v_cvt_pk_bf16_f32 v104, v62, v63
	v_cvt_pk_bf16_f32 v105, v64, v65
	s_waitcnt lgkmcnt(0)
	v_cvt_pk_bf16_f32 v106, v66, v67
	v_cvt_pk_bf16_f32 v107, v68, v69
	v_cvt_pk_bf16_f32 v108, v70, v71
	v_cvt_pk_bf16_f32 v109, v72, v73
	global_store_dwordx4 v74, v[94:97], s[38:39]
	global_store_dwordx4 v75, v[98:101], s[38:39]
	global_store_dwordx4 v76, v[102:105], s[38:39]
	global_store_dwordx4 v77, v[106:109], s[38:39]
	s_lshr_b32 s46, s30, 6
	s_and_b32 s47, s30, 63
	s_mov_b32 s41, s30
	s_lshl_b32 s36, s46, 19
	s_lshl_b32 s37, s47, 7
	s_add_i32 s36, s36, s37
	s_add_u32 s38, s26, s36
	s_addc_u32 s39, s27, 0
	global_load_dwordx4 v[42:45], v4, s[38:39] nt
	s_add_u32 s38, s38, 0x10000
	s_addc_u32 s39, s39, 0
	global_load_dwordx4 v[46:49], v4, s[38:39] nt
	s_add_u32 s38, s38, 0x10000
	s_addc_u32 s39, s39, 0
	global_load_dwordx4 v[50:53], v4, s[38:39] nt
	s_add_u32 s38, s38, 0x10000
	s_addc_u32 s39, s39, 0
	global_load_dwordx4 v[54:57], v4, s[38:39] nt
	s_add_u32 s38, s38, 0x10000
	s_addc_u32 s39, s39, 0
	global_load_dwordx4 v[58:61], v4, s[38:39] nt
	s_add_u32 s38, s38, 0x10000
	s_addc_u32 s39, s39, 0
	global_load_dwordx4 v[62:65], v4, s[38:39] nt
	s_add_u32 s38, s38, 0x10000
	s_addc_u32 s39, s39, 0
	global_load_dwordx4 v[66:69], v4, s[38:39] nt
	s_add_u32 s38, s38, 0x10000
	s_addc_u32 s39, s39, 0
	global_load_dwordx4 v[70:73], v4, s[38:39] nt
	s_addk_i32 s30, 0x800
	s_and_b32 s30, s30, 0x1fff
	s_waitcnt vmcnt(12)
	ds_write_b128 v110, v[10:13]
	ds_write_b128 v111, v[14:17] offset:1024
	ds_write_b128 v112, v[18:21] offset:2048
	ds_write_b128 v113, v[22:25] offset:3072
	ds_write_b128 v114, v[26:29] offset:4096
	ds_write_b128 v115, v[30:33] offset:5120
	ds_write_b128 v116, v[34:37] offset:6144
	ds_write_b128 v117, v[38:41] offset:7168
	ds_read2_b32 v[10:11], v118 offset1:32
	ds_read2_b32 v[12:13], v118 offset0:64 offset1:96
	ds_read2_b32 v[14:15], v118 offset0:128 offset1:160
	ds_read2_b32 v[16:17], v118 offset0:192 offset1:224
	ds_read2_b32 v[18:19], v119 offset1:32
	ds_read2_b32 v[20:21], v119 offset0:64 offset1:96
	ds_read2_b32 v[22:23], v119 offset0:128 offset1:160
	ds_read2_b32 v[24:25], v119 offset0:192 offset1:224
	ds_read2_b32 v[26:27], v120 offset1:32
	ds_read2_b32 v[28:29], v120 offset0:64 offset1:96
	ds_read2_b32 v[30:31], v120 offset0:128 offset1:160
	ds_read2_b32 v[32:33], v120 offset0:192 offset1:224
	ds_read2_b32 v[34:35], v121 offset1:32
	ds_read2_b32 v[36:37], v121 offset0:64 offset1:96
	ds_read2_b32 v[38:39], v121 offset0:128 offset1:160
	ds_read2_b32 v[40:41], v121 offset0:192 offset1:224
	s_lshr_b32 s46, s40, 6
	s_and_b32 s47, s40, 63
	s_lshl_b32 s36, s47, 19
	s_lshl_b32 s37, s46, 7
	s_add_i32 s36, s36, s37
	s_add_u32 s38, s28, s36
	s_addc_u32 s39, s29, 0
	s_waitcnt lgkmcnt(12)
	v_cvt_pk_bf16_f32 v78, v10, v11
	v_cvt_pk_bf16_f32 v79, v12, v13
	v_cvt_pk_bf16_f32 v80, v14, v15
	v_cvt_pk_bf16_f32 v81, v16, v17
	s_waitcnt lgkmcnt(8)
	v_cvt_pk_bf16_f32 v82, v18, v19
	v_cvt_pk_bf16_f32 v83, v20, v21
	v_cvt_pk_bf16_f32 v84, v22, v23
	v_cvt_pk_bf16_f32 v85, v24, v25
	s_waitcnt lgkmcnt(4)
	v_cvt_pk_bf16_f32 v86, v26, v27
	v_cvt_pk_bf16_f32 v87, v28, v29
	v_cvt_pk_bf16_f32 v88, v30, v31
	v_cvt_pk_bf16_f32 v89, v32, v33
	s_waitcnt lgkmcnt(0)
	v_cvt_pk_bf16_f32 v90, v34, v35
	v_cvt_pk_bf16_f32 v91, v36, v37
	v_cvt_pk_bf16_f32 v92, v38, v39
	v_cvt_pk_bf16_f32 v93, v40, v41
	global_store_dwordx4 v74, v[78:81], s[38:39]
	global_store_dwordx4 v75, v[82:85], s[38:39]
	global_store_dwordx4 v76, v[86:89], s[38:39]
	global_store_dwordx4 v77, v[90:93], s[38:39]
	s_waitcnt vmcnt(4)
	ds_write_b128 v110, v[42:45]
	ds_write_b128 v111, v[46:49] offset:1024
	ds_write_b128 v112, v[50:53] offset:2048
	ds_write_b128 v113, v[54:57] offset:3072
	ds_write_b128 v114, v[58:61] offset:4096
	ds_write_b128 v115, v[62:65] offset:5120
	ds_write_b128 v116, v[66:69] offset:6144
	ds_write_b128 v117, v[70:73] offset:7168
	ds_read2_b32 v[42:43], v118 offset1:32
	ds_read2_b32 v[44:45], v118 offset0:64 offset1:96
	ds_read2_b32 v[46:47], v118 offset0:128 offset1:160
	ds_read2_b32 v[48:49], v118 offset0:192 offset1:224
	ds_read2_b32 v[50:51], v119 offset1:32
	ds_read2_b32 v[52:53], v119 offset0:64 offset1:96
	ds_read2_b32 v[54:55], v119 offset0:128 offset1:160
	ds_read2_b32 v[56:57], v119 offset0:192 offset1:224
	ds_read2_b32 v[58:59], v120 offset1:32
	ds_read2_b32 v[60:61], v120 offset0:64 offset1:96
	ds_read2_b32 v[62:63], v120 offset0:128 offset1:160
	ds_read2_b32 v[64:65], v120 offset0:192 offset1:224
	ds_read2_b32 v[66:67], v121 offset1:32
	ds_read2_b32 v[68:69], v121 offset0:64 offset1:96
	ds_read2_b32 v[70:71], v121 offset0:128 offset1:160
	ds_read2_b32 v[72:73], v121 offset0:192 offset1:224
	s_lshr_b32 s46, s41, 6
	s_and_b32 s47, s41, 63
	s_lshl_b32 s36, s47, 19
	s_lshl_b32 s37, s46, 7
	s_add_i32 s36, s36, s37
	s_add_u32 s38, s28, s36
	s_addc_u32 s39, s29, 0
	s_waitcnt lgkmcnt(12)
	v_cvt_pk_bf16_f32 v94, v42, v43
	v_cvt_pk_bf16_f32 v95, v44, v45
	v_cvt_pk_bf16_f32 v96, v46, v47
	v_cvt_pk_bf16_f32 v97, v48, v49
	s_waitcnt lgkmcnt(8)
	v_cvt_pk_bf16_f32 v98, v50, v51
	v_cvt_pk_bf16_f32 v99, v52, v53
	v_cvt_pk_bf16_f32 v100, v54, v55
	v_cvt_pk_bf16_f32 v101, v56, v57
	s_waitcnt lgkmcnt(4)
	v_cvt_pk_bf16_f32 v102, v58, v59
	v_cvt_pk_bf16_f32 v103, v60, v61
	v_cvt_pk_bf16_f32 v104, v62, v63
	v_cvt_pk_bf16_f32 v105, v64, v65
	s_waitcnt lgkmcnt(0)
	v_cvt_pk_bf16_f32 v106, v66, v67
	v_cvt_pk_bf16_f32 v107, v68, v69
	v_cvt_pk_bf16_f32 v108, v70, v71
	v_cvt_pk_bf16_f32 v109, v72, v73
	global_store_dwordx4 v74, v[94:97], s[38:39]
	global_store_dwordx4 v75, v[98:101], s[38:39]
	global_store_dwordx4 v76, v[102:105], s[38:39]
	global_store_dwordx4 v77, v[106:109], s[38:39]
	s_waitcnt vmcnt(0) lgkmcnt(0)

.LBB0_58:
	s_andn2_b64 vcc, exec, s[6:7]
	s_cbranch_vccnz .LBB0_62
	s_branch .LBB0_62
	s_load_dwordx2 s[6:7], s[18:19], 0xd8
	s_add_i32 s13, s29, 0xe000
	s_and_b64 s[14:15], s[22:23], exec
	s_cselect_b32 s14, 0x4000000, 0
	v_mov_b32_e32 v33, v5
	s_waitcnt lgkmcnt(0)
	s_add_u32 s14, s6, s14
	s_addc_u32 s15, s7, 0
	s_lshl_b32 s6, s45, 5
	s_and_b32 s6, s6, 0x7e0
	s_and_b32 s7, s13, 0xffc0
	s_lshl_b32 s13, s6, 2
	s_add_u32 s14, s14, s13
	s_addc_u32 s15, s15, 0
	s_mov_b32 s12, 0
	v_lshl_add_u64 v[34:35], s[14:15], 0, v[32:33]
	s_mov_b32 s13, s7
	s_mov_b32 s14, 1
	s_mov_b32 s15, 32
